# adds: last-tile pool-window output rows loaded 5 at a time (was 1 round trip per row); sample attention items rebalanced (WGs that also run a sample pre-pass token take 1 item, the others 3)
# baseline (speedup 1.0000x reference)
.LBB0_586:
	s_or_b64 exec, exec, s[34:35]
	s_waitcnt lgkmcnt(0)
	s_barrier
	v_readlane_b32 s0, v255, 55
	s_cmp_eq_u32 s96, 0x100
	s_cbranch_scc0 .Lattn_stride_orig
	s_movk_i32 s0, 0x80
	s_cmpk_lt_i32 s70, 0x80
	s_cselect_b32 s0, 0x200, s0
	s_add_i32 s37, s37, s0
	s_lshl_b32 s0, s0, 8
	s_add_i32 s36, s36, s0
	s_branch .Lattn_stride_done
.Lattn_stride_orig:
	s_add_i32 s37, s37, s96
	s_add_i32 s36, s36, s0
.Lattn_stride_done:
	s_cmpk_lt_i32 s37, 0x200
	s_cbranch_scc0 .LBB0_571

.LBB0_881:
	v_add_co_u32_e32 v6, vcc, 0xfffea000, v4
	v_lshl_add_u64 v[8:9], v[2:3], 0, s[34:35]
	s_nop 0
	v_addc_co_u32_e32 v7, vcc, -1, v5, vcc
	global_load_dword v245, v[6:7], off
	s_mov_b32 s16, 0xffff0000
	v_add_co_u32_e32 v6, vcc, s16, v4
	s_nop 1
	v_addc_co_u32_e32 v7, vcc, -1, v5, vcc
	global_load_dword v246, v[6:7], off offset:-2048
	s_mov_b32 s16, 0xffff5000
	v_add_co_u32_e32 v6, vcc, s16, v4
	s_nop 1
	v_addc_co_u32_e32 v7, vcc, -1, v5, vcc
	global_load_dword v247, v[6:7], off
	s_movk_i32 s16, 0xb000
	v_add_co_u32_e32 v6, vcc, s16, v4
	s_nop 1
	v_addc_co_u32_e32 v7, vcc, -1, v5, vcc
	global_load_dword v248, v[6:7], off offset:-2048
	global_load_dword v249, v[4:5], off
	s_mov_b64 s[16:17], 0x1b800
	v_lshl_add_u64 v[4:5], v[4:5], 0, s[16:17]
	s_add_u32 s34, s34, 0x5000
	s_addc_u32 s35, s35, 0
	v_add_co_u32_e32 v10, vcc, 0x6280000, v8
	s_nop 1
	v_addc_co_u32_e32 v11, vcc, 0, v9, vcc
	s_waitcnt vmcnt(4)
	v_lshlrev_b32_e32 v6, 16, v245
	v_and_b32_e32 v7, 0xffff0000, v245
	global_store_dwordx2 v[10:11], v[6:7], off
	v_add_co_u32_e32 v10, vcc, 0x6281000, v8
	s_nop 1
	v_addc_co_u32_e32 v11, vcc, 0, v9, vcc
	s_waitcnt vmcnt(4)
	v_lshlrev_b32_e32 v6, 16, v246
	v_and_b32_e32 v7, 0xffff0000, v246
	global_store_dwordx2 v[10:11], v[6:7], off
	v_add_co_u32_e32 v10, vcc, 0x6282000, v8
	s_nop 1
	v_addc_co_u32_e32 v11, vcc, 0, v9, vcc
	s_waitcnt vmcnt(4)
	v_lshlrev_b32_e32 v6, 16, v247
	v_and_b32_e32 v7, 0xffff0000, v247
	global_store_dwordx2 v[10:11], v[6:7], off
	v_add_co_u32_e32 v10, vcc, 0x6283000, v8
	s_nop 1
	v_addc_co_u32_e32 v11, vcc, 0, v9, vcc
	s_waitcnt vmcnt(4)
	v_lshlrev_b32_e32 v6, 16, v248
	v_and_b32_e32 v7, 0xffff0000, v248
	global_store_dwordx2 v[10:11], v[6:7], off
	v_add_co_u32_e32 v10, vcc, 0x6284000, v8
	s_nop 1
	v_addc_co_u32_e32 v11, vcc, 0, v9, vcc
	s_waitcnt vmcnt(4)
	v_lshlrev_b32_e32 v6, 16, v249
	v_and_b32_e32 v7, 0xffff0000, v249
	global_store_dwordx2 v[10:11], v[6:7], off
	s_cmpk_eq_u32 s34, 0xf000
	s_cbranch_scc0 .LBB0_881
	v_readlane_b32 s16, v253, 45
	v_readlane_b32 s17, v253, 46
	s_mov_b64 s[34:35], 0
	s_nop 0
	v_lshl_add_u64 v[2:3], s[16:17], 0, v[34:35]
